# attention A: K/V prefetch no longer drained at the QK MFMAs (Q-fragment wait hoisted before the tile loop); 7 of 8 transposed V fragments per key block prefetched during the softmax
# speedup vs baseline: 1.1011x; 1.0079x over previous
; DI void lds_barrier() { asm volatile("s_waitcnt lgkmcnt(0)\n\ts_barrier" ::: "memory"); }
; template <int VD, bool DIFF>
; DI void attn_dense(const Params& p, const u16* qkv, int ld, u16* o, const float* lam4, const float* subln,
;                            float lam_init, const float* sinks, char* smem) {
;     ...
;         const int qcol = DIFF ? hd * 128 + mm * 64 : hd * 64;
;         const int kcol = DIFF ? 1024 + hd * 128 + mm * 64 : 1024 + (hd >> 3) * 64;
;         const int bh = DIFF ? mm * 8 + hd : hd;
;         bf16x8 qf[4];
; #pragma unroll
;         for (int s = 0; s < 4; ++s) qf[s] = *(const bf16x8*)(qkv + qrow * ld + qcol + 16 * s + 8 * hh);
;         f32x16 O[NDB];
; #pragma unroll
;         for (int d_ = 0; d_ < NDB; ++d_)
; #pragma unroll
;           for (int i = 0; i < 16; ++i) O[d_][i] = 0.f;
;         float l = 0.f;
;         const float bfar = s_relb[15 * 16 + bh];
;         const int lkey = tid >> 3;
;         u32x4 rk, rv[NVL];
;         {
;           const size_t krow = (size_t)b * T + lkey;
;           rk = *(const u32x4*)(qkv + krow * ld + kcol + (tid & 7) * 8);
; #pragma unroll
;           for (int c_ = 0; c_ < NVL; ++c_) rv[c_] = *(const u32x4*)(qkv + krow * ld + vcol + ((tid & 7) * NVL + c_) * 8);
;         }
;         __syncthreads();
;         {
;           char* sK0 = smem; char* sV0 = smem + 9216;
;           *(u32x4*)(sK0 + lkey * 144 + (tid & 7) * 16) = rk;
; #pragma unroll
;           for (int c_ = 0; c_ < NVL; ++c_) *(u32x4*)(sV0 + lkey * VS + ((tid & 7) * NVL + c_) * 16) = rv[c_];
;         }
;         lds_barrier();
.LBB0_877:
	s_lshl_b32 s2, s5, 6
	s_or_b32 s18, s2, s47
	s_lshl_b32 s2, s18, 1
	v_lshl_add_u64 v[0:1], v[154:155], 0, s[2:3]
	global_load_dwordx4 v[120:123], v[0:1], off offset:2048
	global_load_dwordx4 v[128:131], v[158:159], off
	global_load_dwordx4 v[124:127], v[158:159], off offset:16
	v_lshl_add_u64 v[0:1], v[162:163], 0, s[2:3]
	global_load_dwordx4 v[104:107], v[0:1], off
	global_load_dwordx4 v[108:111], v[0:1], off offset:32
	global_load_dwordx4 v[112:115], v[0:1], off offset:64
	global_load_dwordx4 v[116:119], v[0:1], off offset:96
	s_lshl_b32 s2, s5, 5
	s_or_b32 s51, s48, s2
	v_mov_b32_e32 v16, s51
	ds_read_b32 v192, v16 offset:60352
	s_waitcnt lgkmcnt(0)
	s_barrier
	v_mov_b32_e32 v14, v165
	v_mov_b32_e32 v15, v165
	v_mov_b32_e32 v0, v165
	v_mov_b32_e32 v1, v165
	v_mov_b32_e32 v2, v165
	v_mov_b32_e32 v3, v165
	v_mov_b32_e32 v4, v165
	v_mov_b32_e32 v5, v165
	v_mov_b32_e32 v6, v165
	v_mov_b32_e32 v7, v165
	v_mov_b32_e32 v8, v165
	v_mov_b32_e32 v9, v165
	v_mov_b32_e32 v10, v165
	v_mov_b32_e32 v11, v165
	v_mov_b32_e32 v12, v165
	v_mov_b32_e32 v13, v165
	v_mov_b64_e32 v[30:31], v[14:15]
	v_mov_b64_e32 v[46:47], v[14:15]
	v_mov_b64_e32 v[62:63], v[14:15]
	s_xor_b64 s[14:15], s[16:17], -1
	v_mov_b32_e32 v193, 0
	s_lshl_b32 s16, s18, 1
	s_mov_b32 s2, 16
	v_mov_b64_e32 v[28:29], v[12:13]
	v_mov_b64_e32 v[26:27], v[10:11]
	v_mov_b64_e32 v[24:25], v[8:9]
	v_mov_b64_e32 v[22:23], v[6:7]
	v_mov_b64_e32 v[20:21], v[4:5]
	v_mov_b64_e32 v[18:19], v[2:3]
	v_mov_b64_e32 v[16:17], v[0:1]
	v_mov_b64_e32 v[44:45], v[12:13]
	v_mov_b64_e32 v[42:43], v[10:11]
	v_mov_b64_e32 v[40:41], v[8:9]
	v_mov_b64_e32 v[38:39], v[6:7]
	v_mov_b64_e32 v[36:37], v[4:5]
	v_mov_b64_e32 v[34:35], v[2:3]
	v_mov_b64_e32 v[32:33], v[0:1]
	v_mov_b64_e32 v[60:61], v[12:13]
	v_mov_b64_e32 v[58:59], v[10:11]
	v_mov_b64_e32 v[56:57], v[8:9]
	v_mov_b64_e32 v[54:55], v[6:7]
	v_mov_b64_e32 v[52:53], v[4:5]
	v_mov_b64_e32 v[50:51], v[2:3]
	v_mov_b64_e32 v[48:49], v[0:1]
	s_mov_b32 s52, 0
	s_waitcnt vmcnt(6)
	ds_write_b128 v189, v[120:123]
	s_waitcnt vmcnt(5)
	ds_write_b128 v190, v[128:131] offset:9216
	s_waitcnt vmcnt(4)
	ds_write_b128 v190, v[124:127] offset:9232
	s_waitcnt vmcnt(0) lgkmcnt(0)
	s_barrier
	s_branch .LBB0_879

; DI int crow(int i, int hh) { return (i & 3) + 8 * (i >> 2) + 4 * hh; }
; DI f32x16 mfma32(bf16x8 a, bf16x8 b, f32x16 c) { return __builtin_amdgcn_mfma_f32_32x32x16_bf16(a, b, c, 0, 0, 0); }
; template <int VD, bool DIFF>
; DI void attn_dense(const Params& p, const u16* qkv, int ld, u16* o, const float* lam4, const float* subln,
;                            float lam_init, const float* sinks, char* smem) {
;     ...
;             for (int kb = 0; kb < 2; ++kb) {
;               f32x16 S;
; #pragma unroll
;               for (int i = 0; i < 16; ++i) S[i] = 0.f;
; #pragma unroll
;               for (int s = 0; s < 4; ++s) {
;                 bf16x8 a = *(const bf16x8*)(sK + (32 * kb + l31) * 144 + (2 * s + hh) * 16);
;                 S = mfma32(a, qf[s], S);
;               }
;               if (far) {
; #pragma unroll
;                 for (int i = 0; i < 16; ++i) S[i] = __builtin_amdgcn_exp2f(S[i] + bfar);
;               } else {
; #pragma unroll
;                 for (int i = 0; i < 16; ++i) {
;                   const int kl = 32 * kb + crow(i, hh);
;                   S[i] = __builtin_amdgcn_exp2f(S[i] + bias_lookup(s_relb, s_btab, start + kl - qpos, bh));
;                 }
;               }
.LBB0_881:
	s_cmp_eq_u32 s52, 0
	s_cselect_b64 s[20:21], -1, 0
	s_cmp_le_i32 s52, s50
	s_cselect_b64 s[22:23], -1, 0
	s_or_b64 s[22:23], s[20:21], s[22:23]
	s_andn2_b64 vcc, exec, s[22:23]
	s_cbranch_vccnz .LBB0_891
	s_bitcmp1_b32 s52, 0
	s_cselect_b32 s5, 0x7400, 0
	v_or_b32_e32 v64, s5, v134
	v_add_u32_e32 v96, v64, v171
	ds_read_b128 v[64:67], v96
	ds_read_b128 v[68:71], v96 offset:32
	s_sub_i32 s17, s2, 64
	s_and_b64 s[22:23], s[20:21], exec
	s_cselect_b32 s17, 0, s17
	s_waitcnt lgkmcnt(1)
	v_mfma_f32_32x32x16_bf16 v[80:95], v[64:67], v[104:107], 0
	ds_read_b128 v[64:67], v96 offset:64
	s_sub_i32 s22, s17, s6
	s_add_i32 s22, s22, 63
	s_cmpk_gt_i32 s22, 0xffa5
	s_cselect_b64 s[22:23], -1, 0
	v_add_u32_e32 v194, s17, v191
	s_mov_b64 s[26:27], -1
	s_waitcnt lgkmcnt(1)
	v_mfma_f32_32x32x16_bf16 v[80:95], v[68:71], v[108:111], v[80:95]
	ds_read_b128 v[68:71], v96 offset:96
	s_and_b64 vcc, exec, s[22:23]
	s_waitcnt lgkmcnt(1)
	v_mfma_f32_32x32x16_bf16 v[80:95], v[64:67], v[112:115], v[80:95]
	s_waitcnt lgkmcnt(0)
	v_mfma_f32_32x32x16_bf16 v[80:95], v[68:71], v[116:119], v[80:95]
	v_add3_u32 v203, s5, v172, v170
	v_add_u32_e32 v203, v203, v146
	ds_read_b64_tr_b16 v[222:223], v203 offset:9216
	ds_read_b64_tr_b16 v[224:225], v203 offset:11776
	ds_read_b64_tr_b16 v[226:227], v203 offset:14336
	ds_read_b64_tr_b16 v[228:229], v203 offset:16896
	ds_read_b64_tr_b16 v[230:231], v203 offset:9280
	ds_read_b64_tr_b16 v[232:233], v203 offset:11840
	ds_read_b64_tr_b16 v[234:235], v203 offset:14400
	ds_read_b64_tr_b16 v[236:237], v203 offset:16960
	ds_read_b64_tr_b16 v[238:239], v203 offset:9344
	ds_read_b64_tr_b16 v[240:241], v203 offset:11904
	ds_read_b64_tr_b16 v[242:243], v203 offset:14464
	ds_read_b64_tr_b16 v[244:245], v203 offset:17024
	ds_read_b64_tr_b16 v[246:247], v203 offset:9408
	ds_read_b64_tr_b16 v[248:249], v203 offset:11968
	s_cbranch_vccz .LBB0_884
	v_add_u32_e32 v65, 1, v194
	v_add_u32_e32 v66, 2, v194
	v_add_u32_e32 v67, 3, v194
	v_add_u32_e32 v68, 8, v194
	v_add_u32_e32 v69, 9, v194
	v_add_u32_e32 v70, 10, v194
	v_add_u32_e32 v71, 11, v194
	v_med3_i32 v64, v194, s31, v217
	v_med3_i32 v65, v65, s31, v217
	v_med3_i32 v66, v66, s31, v217
	v_med3_i32 v67, v67, s31, v217
	v_med3_i32 v68, v68, s31, v217
	v_med3_i32 v69, v69, s31, v217
	v_med3_i32 v70, v70, s31, v217
	v_med3_i32 v71, v71, s31, v217
	v_add_u32_e32 v64, 0x1f080, v64
	v_add_u32_e32 v65, 0x1f080, v65
	v_add_u32_e32 v66, 0x1f080, v66
	v_add_u32_e32 v67, 0x1f080, v67
	v_add_u32_e32 v68, 0x1f080, v68
	v_add_u32_e32 v69, 0x1f080, v69
	v_add_u32_e32 v70, 0x1f080, v70
	v_add_u32_e32 v71, 0x1f080, v71
	ds_read_u8 v64, v64
	ds_read_u8 v65, v65
	ds_read_u8 v66, v66
	ds_read_u8 v67, v67
	ds_read_u8 v68, v68
	ds_read_u8 v69, v69
	ds_read_u8 v70, v70
	ds_read_u8 v71, v71
	v_add_u32_e32 v72, 16, v194
	v_add_u32_e32 v73, 17, v194
	v_add_u32_e32 v74, 18, v194
	v_add_u32_e32 v75, 19, v194
	v_add_u32_e32 v76, 24, v194
	v_add_u32_e32 v77, 25, v194
	v_add_u32_e32 v78, 26, v194
	v_add_u32_e32 v79, 27, v194
	v_med3_i32 v72, v72, s31, v217
	v_med3_i32 v73, v73, s31, v217
	v_med3_i32 v74, v74, s31, v217
	v_med3_i32 v75, v75, s31, v217
	v_med3_i32 v76, v76, s31, v217
	v_med3_i32 v77, v77, s31, v217
	v_med3_i32 v78, v78, s31, v217
	v_med3_i32 v79, v79, s31, v217
	s_waitcnt lgkmcnt(7)
	v_lshl_add_u32 v64, v64, 6, s51
	s_waitcnt lgkmcnt(6)
	v_lshl_add_u32 v65, v65, 6, s51
	s_waitcnt lgkmcnt(5)
	v_lshl_add_u32 v66, v66, 6, s51
	s_waitcnt lgkmcnt(4)
	v_lshl_add_u32 v67, v67, 6, s51
	s_waitcnt lgkmcnt(3)
	v_lshl_add_u32 v68, v68, 6, s51
	s_waitcnt lgkmcnt(2)
	v_lshl_add_u32 v69, v69, 6, s51
	s_waitcnt lgkmcnt(1)
	v_lshl_add_u32 v70, v70, 6, s51
	s_waitcnt lgkmcnt(0)
	v_lshl_add_u32 v71, v71, 6, s51
	v_add_u32_e32 v72, 0x1f080, v72
	v_add_u32_e32 v73, 0x1f080, v73
	v_add_u32_e32 v74, 0x1f080, v74
	v_add_u32_e32 v75, 0x1f080, v75
	v_add_u32_e32 v76, 0x1f080, v76
	v_add_u32_e32 v77, 0x1f080, v77
	v_add_u32_e32 v78, 0x1f080, v78
	v_add_u32_e32 v79, 0x1f080, v79
	ds_read_b32 v64, v64 offset:59392
	ds_read_b32 v65, v65 offset:59392
	ds_read_b32 v66, v66 offset:59392
	ds_read_b32 v67, v67 offset:59392
	ds_read_b32 v68, v68 offset:59392
	ds_read_b32 v69, v69 offset:59392
	ds_read_b32 v70, v70 offset:59392
	ds_read_b32 v71, v71 offset:59392
	ds_read_u8 v72, v72
	ds_read_u8 v73, v73
	ds_read_u8 v74, v74
	ds_read_u8 v75, v75
	ds_read_u8 v76, v76
	ds_read_u8 v77, v77
	ds_read_u8 v78, v78
	ds_read_u8 v79, v79
	s_waitcnt lgkmcnt(7)
	v_lshl_add_u32 v72, v72, 6, s51
	s_waitcnt lgkmcnt(6)
	v_lshl_add_u32 v73, v73, 6, s51
	s_waitcnt lgkmcnt(5)
	v_lshl_add_u32 v74, v74, 6, s51
	s_waitcnt lgkmcnt(4)
	v_lshl_add_u32 v75, v75, 6, s51
	s_waitcnt lgkmcnt(3)
	v_lshl_add_u32 v76, v76, 6, s51
	s_waitcnt lgkmcnt(2)
	v_lshl_add_u32 v77, v77, 6, s51
	s_waitcnt lgkmcnt(1)
	v_lshl_add_u32 v78, v78, 6, s51
	s_waitcnt lgkmcnt(0)
	v_lshl_add_u32 v79, v79, 6, s51
	ds_read_b32 v72, v72 offset:59392
	ds_read_b32 v73, v73 offset:59392
	ds_read_b32 v74, v74 offset:59392
	ds_read_b32 v75, v75 offset:59392
	ds_read_b32 v76, v76 offset:59392
	ds_read_b32 v77, v77 offset:59392
	ds_read_b32 v78, v78 offset:59392
	ds_read_b32 v79, v79 offset:59392
	v_add_f32_e32 v64, v80, v64
	v_add_f32_e32 v65, v81, v65
	v_add_f32_e32 v66, v82, v66
	v_add_f32_e32 v67, v83, v67
	v_add_f32_e32 v68, v84, v68
	v_add_f32_e32 v69, v85, v69
	v_add_f32_e32 v70, v86, v70
	v_add_f32_e32 v71, v87, v71
	s_waitcnt lgkmcnt(7)
	v_add_f32_e32 v72, v88, v72
	s_waitcnt lgkmcnt(6)
	v_add_f32_e32 v73, v89, v73
	s_waitcnt lgkmcnt(5)
	v_add_f32_e32 v74, v90, v74
	s_waitcnt lgkmcnt(4)
	v_add_f32_e32 v75, v91, v75
	s_waitcnt lgkmcnt(3)
	v_add_f32_e32 v76, v92, v76
	s_waitcnt lgkmcnt(2)
	v_add_f32_e32 v77, v93, v77
	s_waitcnt lgkmcnt(1)
	v_add_f32_e32 v78, v94, v78
	v_exp_f32_e32 v64, v64
	v_exp_f32_e32 v65, v65
	v_exp_f32_e32 v66, v66
	v_exp_f32_e32 v67, v67
	v_exp_f32_e32 v68, v68
	v_exp_f32_e32 v69, v69
	v_exp_f32_e32 v70, v70
	v_exp_f32_e32 v71, v71
	v_exp_f32_e32 v72, v72
	v_exp_f32_e32 v73, v73
	v_exp_f32_e32 v74, v74
	v_exp_f32_e32 v75, v75
	v_exp_f32_e32 v76, v76
	v_exp_f32_e32 v77, v77
	v_exp_f32_e32 v78, v78
	s_waitcnt lgkmcnt(0)
	v_add_f32_e32 v79, v95, v79
	s_mov_b64 s[26:27], 0

; DI int crow(int i, int hh) { return (i & 3) + 8 * (i >> 2) + 4 * hh; }
; DI f32x16 mfma32(bf16x8 a, bf16x8 b, f32x16 c) { return __builtin_amdgcn_mfma_f32_32x32x16_bf16(a, b, c, 0, 0, 0); }
; template <int VD, bool DIFF>
; DI void attn_dense(const Params& p, const u16* qkv, int ld, u16* o, const float* lam4, const float* subln,
;                            float lam_init, const float* sinks, char* smem) {
;     ...
;             for (int kb = 0; kb < 2; ++kb) {
;               f32x16 S;
; #pragma unroll
;               for (int i = 0; i < 16; ++i) S[i] = 0.f;
; #pragma unroll
;               for (int s = 0; s < 4; ++s) {
;                 bf16x8 a = *(const bf16x8*)(sK + (32 * kb + l31) * 144 + (2 * s + hh) * 16);
;                 S = mfma32(a, qf[s], S);
;               }
;               if (far) {
; #pragma unroll
;                 for (int i = 0; i < 16; ++i) S[i] = __builtin_amdgcn_exp2f(S[i] + bfar);
;               } else {
; #pragma unroll
;                 for (int i = 0; i < 16; ++i) {
;                   const int kl = 32 * kb + crow(i, hh);
;                   S[i] = __builtin_amdgcn_exp2f(S[i] + bias_lookup(s_relb, s_btab, start + kl - qpos, bh));
;                 }
;               }
;               if (valid < 64) {
; #pragma unroll
;                 for (int i = 0; i < 16; ++i) {
;                   const int kl = 32 * kb + crow(i, hh);
;                   S[i] = kl < valid ? S[i] : 0.f;
;                 }
;               }
; #pragma unroll
;               for (int i = 0; i < 16; ++i) l += S[i];
;               bf16x8 pf[2];
; #pragma unroll
;               for (int s2 = 0; s2 < 2; ++s2)
;                 pf[s2] = mk8(pack2(S[8 * s2], S[8 * s2 + 1]), pack2(S[8 * s2 + 2], S[8 * s2 + 3]),
;                              pack2(S[8 * s2 + 4], S[8 * s2 + 5]), pack2(S[8 * s2 + 6], S[8 * s2 + 7]));
; #pragma unroll
;               for (int d_ = 0; d_ < NDB; ++d_) {
; #pragma unroll
;                 for (int s2 = 0; s2 < 2; ++s2) {
;                   const int k0 = 32 * kb + 16 * s2 + 4 * hh + q4;
;                   s16x4 lo = tr_read(sV + k0 * VS + (32 * d_ + 16 * blk) * 2 + 8 * p4);
;                   s16x4 hi = tr_read(sV + (k0 + 8) * VS + (32 * d_ + 16 * blk) * 2 + 8 * p4);
;                   O[d_] = mfma32(cat8(lo, hi), pf[s2], O[d_]);
;                 }
;               }
;               __builtin_amdgcn_sched_barrier(0);
.LBB0_886:
	s_nop 8
	v_add3_u32 v80, s5, v172, v170
	v_add_u32_e32 v157, v80, v146
	ds_read_b64_tr_b16 v[80:81], v157 offset:14528
	ds_read_b64_tr_b16 v[82:83], v157 offset:17088
	v_cndmask_b32_e64 v199, v75, 0, s[20:21]
	v_cndmask_b32_e64 v200, v74, 0, s[20:21]
	v_cndmask_b32_e64 v201, v73, 0, s[20:21]
	v_cndmask_b32_e64 v202, v72, 0, s[20:21]
	v_cvt_pk_bf16_f32 v72, v64, v65
	v_cvt_pk_bf16_f32 v73, v66, v67
	v_cvt_pk_bf16_f32 v74, v68, v69
	v_cvt_pk_bf16_f32 v75, v70, v71
	v_exp_f32_e32 v79, v79
	v_cndmask_b32_e64 v196, v78, 0, s[20:21]
	s_waitcnt lgkmcnt(2)
	v_mfma_f32_32x32x16_bf16 v[48:63], v[222:225], v[72:75], v[48:63]
	v_cndmask_b32_e64 v195, v79, 0, s[20:21]
	v_cndmask_b32_e64 v197, v77, 0, s[20:21]
	v_cndmask_b32_e64 v198, v76, 0, s[20:21]
	v_cvt_pk_bf16_f32 v76, v202, v201
	v_cvt_pk_bf16_f32 v77, v200, v199
	v_cvt_pk_bf16_f32 v78, v198, v197
	v_cvt_pk_bf16_f32 v79, v196, v195
	s_nop 0
	s_nop 0
	v_mfma_f32_32x32x16_bf16 v[48:63], v[226:229], v[76:79], v[48:63]
	v_mfma_f32_32x32x16_bf16 v[32:47], v[230:233], v[72:75], v[32:47]
	v_mfma_f32_32x32x16_bf16 v[32:47], v[234:237], v[76:79], v[32:47]
	v_mfma_f32_32x32x16_bf16 v[16:31], v[238:241], v[72:75], v[16:31]
	v_mfma_f32_32x32x16_bf16 v[16:31], v[242:245], v[76:79], v[16:31]
	v_mfma_f32_32x32x16_bf16 v[0:15], v[246:249], v[72:75], v[0:15]
	s_waitcnt lgkmcnt(0)
	v_mfma_f32_32x32x16_bf16 v[0:15], v[80:83], v[76:79], v[0:15]
	ds_read_b128 v[72:75], v96 offset:4608
	ds_read_b128 v[88:91], v96 offset:4640
	s_andn2_b64 vcc, exec, s[22:23]
	s_mov_b64 s[22:23], -1
	s_waitcnt lgkmcnt(1)
	v_mfma_f32_32x32x16_bf16 v[72:87], v[72:75], v[104:107], 0
	s_waitcnt lgkmcnt(0)
	v_mfma_f32_32x32x16_bf16 v[72:87], v[88:91], v[108:111], v[72:87]
	ds_read_b128 v[88:91], v96 offset:4672
	ds_read_b128 v[92:95], v96 offset:4704
	s_waitcnt lgkmcnt(1)
	v_mfma_f32_32x32x16_bf16 v[72:87], v[88:91], v[112:115], v[72:87]
	s_waitcnt lgkmcnt(0)
	v_mfma_f32_32x32x16_bf16 v[72:87], v[92:95], v[116:119], v[72:87]
	ds_read_b64_tr_b16 v[222:223], v157 offset:19456
	ds_read_b64_tr_b16 v[224:225], v157 offset:22016
	ds_read_b64_tr_b16 v[226:227], v157 offset:24576
	ds_read_b64_tr_b16 v[228:229], v157 offset:27136
	ds_read_b64_tr_b16 v[230:231], v157 offset:19520
	ds_read_b64_tr_b16 v[232:233], v157 offset:22080
	ds_read_b64_tr_b16 v[234:235], v157 offset:24640
	ds_read_b64_tr_b16 v[236:237], v157 offset:27200
	ds_read_b64_tr_b16 v[238:239], v157 offset:19584
	ds_read_b64_tr_b16 v[240:241], v157 offset:22144
	ds_read_b64_tr_b16 v[242:243], v157 offset:24704
	ds_read_b64_tr_b16 v[244:245], v157 offset:27264
	ds_read_b64_tr_b16 v[246:247], v157 offset:19648
	ds_read_b64_tr_b16 v[248:249], v157 offset:22208
	s_cbranch_vccnz .LBB0_888
; DI int crow(int i, int hh) { return (i & 3) + 8 * (i >> 2) + 4 * hh; }
; template <int VD, bool DIFF>
; DI void attn_dense(const Params& p, const u16* qkv, int ld, u16* o, const float* lam4, const float* subln,
;                            float lam_init, const float* sinks, char* smem) {
;     ...
;               } else {
; #pragma unroll
;                 for (int i = 0; i < 16; ++i) {
;                   const int kl = 32 * kb + crow(i, hh);
;                   S[i] = __builtin_amdgcn_exp2f(S[i] + bias_lookup(s_relb, s_btab, start + kl - qpos, bh));
;                 }
;               }
	v_add_u32_e32 v88, 32, v194
	v_add_u32_e32 v89, 33, v194
	v_add_u32_e32 v90, 34, v194
	v_add_u32_e32 v91, 35, v194
	v_add_u32_e32 v92, 40, v194
	v_add_u32_e32 v93, 41, v194
	v_add_u32_e32 v94, 42, v194
	v_add_u32_e32 v95, 43, v194
	v_med3_i32 v88, v88, s31, v217
	v_med3_i32 v89, v89, s31, v217
	v_med3_i32 v90, v90, s31, v217
	v_med3_i32 v91, v91, s31, v217
	v_med3_i32 v92, v92, s31, v217
	v_med3_i32 v93, v93, s31, v217
	v_med3_i32 v94, v94, s31, v217
	v_med3_i32 v95, v95, s31, v217
	v_add_u32_e32 v88, 0x1f080, v88
	v_add_u32_e32 v89, 0x1f080, v89
	v_add_u32_e32 v90, 0x1f080, v90
	v_add_u32_e32 v91, 0x1f080, v91
	v_add_u32_e32 v92, 0x1f080, v92
	v_add_u32_e32 v93, 0x1f080, v93
	v_add_u32_e32 v94, 0x1f080, v94
	v_add_u32_e32 v95, 0x1f080, v95
	ds_read_u8 v88, v88
	ds_read_u8 v89, v89
	ds_read_u8 v90, v90
	ds_read_u8 v91, v91
	ds_read_u8 v92, v92
	ds_read_u8 v93, v93
	ds_read_u8 v94, v94
	ds_read_u8 v95, v95
	v_add_u32_e32 v96, 48, v194
	v_add_u32_e32 v97, 49, v194
	v_add_u32_e32 v98, 50, v194
	v_add_u32_e32 v99, 51, v194
	v_add_u32_e32 v100, 56, v194
	v_add_u32_e32 v101, 57, v194
	v_add_u32_e32 v102, 58, v194
	v_add_u32_e32 v103, 59, v194
	v_med3_i32 v96, v96, s31, v217
	v_med3_i32 v97, v97, s31, v217
	v_med3_i32 v98, v98, s31, v217
	v_med3_i32 v99, v99, s31, v217
	v_med3_i32 v100, v100, s31, v217
	v_med3_i32 v101, v101, s31, v217
	v_med3_i32 v102, v102, s31, v217
	v_med3_i32 v103, v103, s31, v217
	s_waitcnt lgkmcnt(7)
	v_lshl_add_u32 v88, v88, 6, s51
	s_waitcnt lgkmcnt(6)
	v_lshl_add_u32 v89, v89, 6, s51
	s_waitcnt lgkmcnt(5)
	v_lshl_add_u32 v90, v90, 6, s51
	s_waitcnt lgkmcnt(4)
	v_lshl_add_u32 v91, v91, 6, s51
	s_waitcnt lgkmcnt(3)
	v_lshl_add_u32 v92, v92, 6, s51
	s_waitcnt lgkmcnt(2)
	v_lshl_add_u32 v93, v93, 6, s51
	s_waitcnt lgkmcnt(1)
	v_lshl_add_u32 v94, v94, 6, s51
	s_waitcnt lgkmcnt(0)
	v_lshl_add_u32 v95, v95, 6, s51
	v_add_u32_e32 v96, 0x1f080, v96
	v_add_u32_e32 v97, 0x1f080, v97
	v_add_u32_e32 v98, 0x1f080, v98
	v_add_u32_e32 v99, 0x1f080, v99
	v_add_u32_e32 v100, 0x1f080, v100
	v_add_u32_e32 v101, 0x1f080, v101
	v_add_u32_e32 v102, 0x1f080, v102
	v_add_u32_e32 v103, 0x1f080, v103
	ds_read_b32 v88, v88 offset:59392
	ds_read_b32 v89, v89 offset:59392
	ds_read_b32 v90, v90 offset:59392
	ds_read_b32 v91, v91 offset:59392
	ds_read_b32 v92, v92 offset:59392
	ds_read_b32 v93, v93 offset:59392
	ds_read_b32 v94, v94 offset:59392
	ds_read_b32 v95, v95 offset:59392
	ds_read_u8 v96, v96
	ds_read_u8 v97, v97
	ds_read_u8 v98, v98
	ds_read_u8 v99, v99
	ds_read_u8 v100, v100
	ds_read_u8 v101, v101
	ds_read_u8 v102, v102
	ds_read_u8 v103, v103
	s_waitcnt lgkmcnt(7)
	v_lshl_add_u32 v96, v96, 6, s51
	s_waitcnt lgkmcnt(6)
	v_lshl_add_u32 v97, v97, 6, s51
	s_waitcnt lgkmcnt(5)
	v_lshl_add_u32 v98, v98, 6, s51
	s_waitcnt lgkmcnt(4)
	v_lshl_add_u32 v99, v99, 6, s51
	s_waitcnt lgkmcnt(3)
	v_lshl_add_u32 v100, v100, 6, s51
	s_waitcnt lgkmcnt(2)
	v_lshl_add_u32 v101, v101, 6, s51
	s_waitcnt lgkmcnt(1)
	v_lshl_add_u32 v102, v102, 6, s51
	s_waitcnt lgkmcnt(0)
	v_lshl_add_u32 v103, v103, 6, s51
	ds_read_b32 v96, v96 offset:59392
	ds_read_b32 v97, v97 offset:59392
	ds_read_b32 v98, v98 offset:59392
	ds_read_b32 v99, v99 offset:59392
	ds_read_b32 v100, v100 offset:59392
	ds_read_b32 v101, v101 offset:59392
	ds_read_b32 v102, v102 offset:59392
	ds_read_b32 v103, v103 offset:59392
	v_add_f32_e32 v88, v72, v88
	v_add_f32_e32 v89, v73, v89
	v_add_f32_e32 v90, v74, v90
	v_add_f32_e32 v91, v75, v91
	v_add_f32_e32 v92, v76, v92
	v_add_f32_e32 v93, v77, v93
	v_add_f32_e32 v94, v78, v94
	v_add_f32_e32 v95, v79, v95
	s_waitcnt lgkmcnt(7)
	v_add_f32_e32 v96, v80, v96
	s_waitcnt lgkmcnt(6)
	v_add_f32_e32 v97, v81, v97
	s_waitcnt lgkmcnt(5)
	v_add_f32_e32 v98, v82, v98
	s_waitcnt lgkmcnt(4)
	v_add_f32_e32 v99, v83, v99
	s_waitcnt lgkmcnt(3)
	v_add_f32_e32 v100, v84, v100
	s_waitcnt lgkmcnt(2)
	v_add_f32_e32 v101, v85, v101
	s_waitcnt lgkmcnt(1)
	v_add_f32_e32 v102, v86, v102
	v_exp_f32_e32 v88, v88
	v_exp_f32_e32 v89, v89
	v_exp_f32_e32 v90, v90
	v_exp_f32_e32 v91, v91
	v_exp_f32_e32 v92, v92
	v_exp_f32_e32 v93, v93
	v_exp_f32_e32 v94, v94
	v_exp_f32_e32 v95, v95
	v_exp_f32_e32 v96, v96
	v_exp_f32_e32 v97, v97
	v_exp_f32_e32 v98, v98
	v_exp_f32_e32 v99, v99
	v_exp_f32_e32 v100, v100
	v_exp_f32_e32 v101, v101
	v_exp_f32_e32 v102, v102
	s_waitcnt lgkmcnt(0)
	v_add_f32_e32 v103, v87, v103
	s_mov_b64 s[22:23], 0

; DI int crow(int i, int hh) { return (i & 3) + 8 * (i >> 2) + 4 * hh; }
; DI f32x16 mfma32(bf16x8 a, bf16x8 b, f32x16 c) { return __builtin_amdgcn_mfma_f32_32x32x16_bf16(a, b, c, 0, 0, 0); }
; DI bf16x8 cat8(s16x4 lo, s16x4 hi) { return __builtin_shufflevector(lo, hi, 0, 1, 2, 3, 4, 5, 6, 7); }
; template <int VD, bool DIFF>
; DI void attn_dense(const Params& p, const u16* qkv, int ld, u16* o, const float* lam4, const float* subln,
;                            float lam_init, const float* sinks, char* smem) {
;     ...
;               if (valid < 64) {
; #pragma unroll
;                 for (int i = 0; i < 16; ++i) {
;                   const int kl = 32 * kb + crow(i, hh);
;                   S[i] = kl < valid ? S[i] : 0.f;
;                 }
;               }
; #pragma unroll
;               for (int i = 0; i < 16; ++i) l += S[i];
;               bf16x8 pf[2];
; #pragma unroll
;               for (int s2 = 0; s2 < 2; ++s2)
;                 pf[s2] = mk8(pack2(S[8 * s2], S[8 * s2 + 1]), pack2(S[8 * s2 + 2], S[8 * s2 + 3]),
;                              pack2(S[8 * s2 + 4], S[8 * s2 + 5]), pack2(S[8 * s2 + 6], S[8 * s2 + 7]));
; #pragma unroll
;               for (int d_ = 0; d_ < NDB; ++d_) {
; #pragma unroll
;                 for (int s2 = 0; s2 < 2; ++s2) {
;                   const int k0 = 32 * kb + 16 * s2 + 4 * hh + q4;
;                   s16x4 lo = tr_read(sV + k0 * VS + (32 * d_ + 16 * blk) * 2 + 8 * p4);
;                   s16x4 hi = tr_read(sV + (k0 + 8) * VS + (32 * d_ + 16 * blk) * 2 + 8 * p4);
;                   O[d_] = mfma32(cat8(lo, hi), pf[s2], O[d_]);
;                 }
;               }
;               __builtin_amdgcn_sched_barrier(0);
.LBB0_890:
	v_add_f32_e32 v64, v193, v64
	v_add_f32_e32 v64, v65, v64
	v_add_f32_e32 v64, v66, v64
	v_add_f32_e32 v64, v67, v64
	v_add_f32_e32 v64, v68, v64
	v_add_f32_e32 v64, v69, v64
	v_add_f32_e32 v64, v70, v64
	v_add_f32_e32 v64, v71, v64
	v_add_f32_e32 v64, v202, v64
	v_add_f32_e32 v64, v201, v64
	v_add_f32_e32 v64, v200, v64
	v_add_f32_e32 v64, v199, v64
	v_add_f32_e32 v64, v198, v64
	v_add_f32_e32 v64, v197, v64
	v_add_f32_e32 v64, v196, v64
	v_add_f32_e32 v72, v195, v64
	v_cndmask_b32_e64 v88, v88, 0, s[20:21]
	v_cndmask_b32_e64 v87, v89, 0, s[20:21]
	v_add_f32_e32 v72, v72, v88
	v_cndmask_b32_e64 v86, v90, 0, s[20:21]
	v_add_f32_e32 v72, v87, v72
	v_cndmask_b32_e64 v85, v91, 0, s[20:21]
	v_add_f32_e32 v72, v86, v72
	v_cndmask_b32_e64 v84, v92, 0, s[20:21]
	v_add_f32_e32 v72, v85, v72
	v_cndmask_b32_e64 v83, v93, 0, s[20:21]
	v_add_f32_e32 v72, v84, v72
	v_cndmask_b32_e64 v82, v94, 0, s[20:21]
	v_add_f32_e32 v72, v83, v72
	v_cndmask_b32_e64 v81, v95, 0, s[20:21]
	v_add_f32_e32 v72, v82, v72
	v_cndmask_b32_e64 v80, v96, 0, s[20:21]
	v_add_f32_e32 v72, v81, v72
	v_cndmask_b32_e64 v79, v97, 0, s[20:21]
	v_add_f32_e32 v72, v80, v72
	v_exp_f32_e32 v64, v103
	v_cndmask_b32_e64 v78, v98, 0, s[20:21]
	v_add_f32_e32 v72, v79, v72
	v_cndmask_b32_e64 v77, v99, 0, s[20:21]
	v_add_f32_e32 v72, v78, v72
	v_cndmask_b32_e64 v75, v100, 0, s[20:21]
	v_add_f32_e32 v72, v77, v72
	v_cndmask_b32_e64 v74, v101, 0, s[20:21]
	v_add_f32_e32 v72, v75, v72
	v_cndmask_b32_e64 v76, v64, 0, s[20:21]
	v_cndmask_b32_e64 v73, v102, 0, s[20:21]
	v_add_f32_e32 v72, v74, v72
	v_cvt_pk_bf16_f32 v65, v78, v77
	v_cvt_pk_bf16_f32 v66, v75, v74
	v_cvt_pk_bf16_f32 v67, v73, v76
	v_add_f32_e32 v77, v73, v72
	ds_read_b64_tr_b16 v[72:73], v157 offset:24768
	ds_read_b64_tr_b16 v[74:75], v157 offset:27328
	v_cvt_pk_bf16_f32 v68, v88, v87
	v_cvt_pk_bf16_f32 v69, v86, v85
	v_cvt_pk_bf16_f32 v70, v84, v83
	v_cvt_pk_bf16_f32 v71, v82, v81
	v_cvt_pk_bf16_f32 v64, v80, v79
	v_add_f32_e32 v193, v76, v77
	s_waitcnt lgkmcnt(2)
	v_mfma_f32_32x32x16_bf16 v[48:63], v[222:225], v[68:71], v[48:63]
	v_mfma_f32_32x32x16_bf16 v[48:63], v[226:229], v[64:67], v[48:63]
	v_mfma_f32_32x32x16_bf16 v[32:47], v[230:233], v[68:71], v[32:47]
	v_mfma_f32_32x32x16_bf16 v[32:47], v[234:237], v[64:67], v[32:47]
	v_mfma_f32_32x32x16_bf16 v[16:31], v[238:241], v[68:71], v[16:31]
	v_mfma_f32_32x32x16_bf16 v[16:31], v[242:245], v[64:67], v[16:31]
	v_mfma_f32_32x32x16_bf16 v[0:15], v[246:249], v[68:71], v[0:15]
	s_waitcnt lgkmcnt(0)
	v_mfma_f32_32x32x16_bf16 v[0:15], v[72:75], v[64:67], v[0:15]
